# merge row loop hand-scheduled: a row's six loads issued together one row ahead (was five serialized memory round trips per row), SiLU divisions of a dword's two halves interleaved
# speedup vs baseline: 1.0155x; 1.0155x over previous
.LBB0_1100:
	v_lshl_add_u64 v[2:3], v[2:3], 0, v[164:165]
	v_lshl_add_u64 v[0:1], v[0:1], 0, v[164:165]
	s_mov_b64 s[10:11], 0x800
	global_load_dwordx4 v[194:197], v[2:3], off
	global_load_dwordx4 v[198:201], v[2:3], off offset:1024
	global_load_dwordx4 v[202:205], v[0:1], off offset:1664
	global_load_dwordx4 v[206:209], v[0:1], off offset:2688
	global_load_dwordx4 v[210:213], v[0:1], off offset:3712
	v_lshl_add_u64 v[4:5], v[0:1], 0, s[10:11]
	global_load_dwordx4 v[214:217], v[4:5], off offset:2688
	v_mov_b32_e32 v250, v2
	v_mov_b32_e32 v251, v3
	s_mov_b64 s[8:9], 0x1000
	v_lshl_add_u64 v[2:3], v[2:3], 0, s[8:9]
	s_mov_b64 s[8:9], 0x1700
	v_lshl_add_u64 v[0:1], v[0:1], 0, s[8:9]
.Lmg_loop:
	global_load_dwordx4 v[218:221], v[2:3], off
	global_load_dwordx4 v[222:225], v[2:3], off offset:1024
	global_load_dwordx4 v[226:229], v[0:1], off offset:1664
	global_load_dwordx4 v[230:233], v[0:1], off offset:2688
	global_load_dwordx4 v[234:237], v[0:1], off offset:3712
	v_lshl_add_u64 v[4:5], v[0:1], 0, s[10:11]
	global_load_dwordx4 v[238:241], v[4:5], off offset:2688
	v_mov_b32_e32 v252, v2
	v_mov_b32_e32 v253, v3
	s_mov_b64 s[8:9], 0x1000
	v_lshl_add_u64 v[2:3], v[2:3], 0, s[8:9]
	s_mov_b64 s[8:9], 0x1700
	v_lshl_add_u64 v[0:1], v[0:1], 0, s[8:9]
	v_add_u32_e32 v66, s0, v46
	ds_read_b128 v[242:245], v66
	ds_read_b128 v[246:249], v66 offset:1024
	s_waitcnt vmcnt(6)
	s_waitcnt lgkmcnt(0)
	v_lshlrev_b32_e32 v6, 16, v242
	v_lshlrev_b32_e32 v7, 16, v194
	v_and_b32_e32 v8, 0xffff0000, v242
	v_and_b32_e32 v9, 0xffff0000, v194
	v_lshlrev_b32_e32 v10, 16, v243
	v_lshlrev_b32_e32 v11, 16, v195
	v_and_b32_e32 v12, 0xffff0000, v243
	v_and_b32_e32 v13, 0xffff0000, v195
	v_lshlrev_b32_e32 v14, 16, v244
	v_lshlrev_b32_e32 v15, 16, v196
	v_and_b32_e32 v16, 0xffff0000, v244
	v_and_b32_e32 v17, 0xffff0000, v196
	v_lshlrev_b32_e32 v18, 16, v245
	v_lshlrev_b32_e32 v19, 16, v197
	v_and_b32_e32 v20, 0xffff0000, v245
	v_and_b32_e32 v21, 0xffff0000, v197
	v_lshlrev_b32_e32 v22, 16, v246
	v_lshlrev_b32_e32 v23, 16, v198
	v_and_b32_e32 v24, 0xffff0000, v246
	v_and_b32_e32 v25, 0xffff0000, v198
	v_lshlrev_b32_e32 v26, 16, v247
	v_lshlrev_b32_e32 v27, 16, v199
	v_and_b32_e32 v28, 0xffff0000, v247
	v_and_b32_e32 v29, 0xffff0000, v199
	v_lshlrev_b32_e32 v30, 16, v248
	v_lshlrev_b32_e32 v31, 16, v200
	v_and_b32_e32 v32, 0xffff0000, v248
	v_and_b32_e32 v33, 0xffff0000, v200
	v_lshlrev_b32_e32 v34, 16, v249
	v_lshlrev_b32_e32 v35, 16, v201
	v_and_b32_e32 v36, 0xffff0000, v249
	v_and_b32_e32 v37, 0xffff0000, v201
	v_pk_mul_f32 v[38:39], v[8:9], v[8:9]
	v_pk_fma_f32 v[38:39], v[6:7], v[6:7], v[38:39]
	v_pk_fma_f32 v[38:39], v[10:11], v[10:11], v[38:39]
	v_pk_fma_f32 v[38:39], v[12:13], v[12:13], v[38:39]
	v_pk_fma_f32 v[38:39], v[14:15], v[14:15], v[38:39]
	v_pk_fma_f32 v[38:39], v[16:17], v[16:17], v[38:39]
	v_pk_fma_f32 v[38:39], v[18:19], v[18:19], v[38:39]
	v_pk_fma_f32 v[38:39], v[20:21], v[20:21], v[38:39]
	v_pk_fma_f32 v[38:39], v[22:23], v[22:23], v[38:39]
	v_pk_fma_f32 v[38:39], v[24:25], v[24:25], v[38:39]
	v_pk_fma_f32 v[38:39], v[26:27], v[26:27], v[38:39]
	v_pk_fma_f32 v[38:39], v[28:29], v[28:29], v[38:39]
	v_pk_mul_f32 v[48:49], v[30:31], v[30:31]
	v_pk_add_f32 v[38:39], v[48:49], v[38:39]
	v_pk_mul_f32 v[48:49], v[32:33], v[32:33]
	v_pk_add_f32 v[38:39], v[48:49], v[38:39]
	v_pk_mul_f32 v[48:49], v[34:35], v[34:35]
	v_pk_add_f32 v[38:39], v[48:49], v[38:39]
	v_pk_mul_f32 v[48:49], v[36:37], v[36:37]
	v_pk_add_f32 v[38:39], v[48:49], v[38:39]
	v_mov_b32_e32 v48, v38
	v_mov_b32_e32 v49, v39
	s_nop 1
	v_permlane32_swap_b32_e32 v38, v48
	v_permlane32_swap_b32_e32 v39, v49
	s_nop 0
	v_add_f32_e32 v38, v38, v48
	v_add_f32_e32 v39, v39, v49
	v_mov_b32_e32 v48, v38
	v_mov_b32_e32 v49, v39
	s_nop 1
	v_permlane16_swap_b32_e32 v38, v48
	v_permlane16_swap_b32_e32 v39, v49
	s_nop 0
	v_add_f32_e32 v38, v38, v48
	v_add_f32_e32 v39, v39, v49
	s_nop 1
	v_add_f32_dpp v38, v38, v38 row_ror:8 row_mask:0xf bank_mask:0xf
	v_add_f32_dpp v39, v39, v39 row_ror:8 row_mask:0xf bank_mask:0xf
	s_nop 1
	v_add_f32_dpp v38, v38, v38 row_ror:4 row_mask:0xf bank_mask:0xf
	v_add_f32_dpp v39, v39, v39 row_ror:4 row_mask:0xf bank_mask:0xf
	s_nop 1
	v_add_f32_dpp v38, v38, v38 row_ror:2 row_mask:0xf bank_mask:0xf
	v_add_f32_dpp v39, v39, v39 row_ror:2 row_mask:0xf bank_mask:0xf
	s_nop 1
	v_add_f32_dpp v38, v38, v38 row_ror:1 row_mask:0xf bank_mask:0xf
	v_add_f32_dpp v39, v39, v39 row_ror:1 row_mask:0xf bank_mask:0xf
	s_nop 1
	v_pk_fma_f32 v[38:39], v[38:39], s[20:21], v[166:167] op_sel_hi:[1,0,0]
	s_nop 0
	v_mul_f32_e32 v47, 0x4b800000, v39
	v_cmp_gt_f32_e64 s[10:11], s58, v39
	v_cmp_gt_f32_e32 vcc, s58, v38
	s_nop 1
	v_cndmask_b32_e64 v39, v39, v47, s[10:11]
	v_rsq_f32_e32 v39, v39
	s_nop 0
	v_mul_f32_e32 v47, 0x45800000, v39
	v_cndmask_b32_e64 v64, v39, v47, s[10:11]
	v_mul_f32_e32 v39, 0x4b800000, v38
	v_cndmask_b32_e32 v38, v38, v39, vcc
	v_rsq_f32_e32 v38, v38
	s_nop 0
	v_mul_f32_e32 v39, 0x45800000, v38
	v_cndmask_b32_e32 v65, v38, v39, vcc
	s_mov_b64 s[10:11], 0x800
	v_mul_f32_e32 v6, v65, v6
	v_mul_f32_e32 v7, v64, v7
	v_mul_f32_e32 v8, v65, v8
	v_mul_f32_e32 v9, v64, v9
	v_mul_f32_e32 v10, v65, v10
	v_mul_f32_e32 v11, v64, v11
	v_mul_f32_e32 v12, v65, v12
	v_mul_f32_e32 v13, v64, v13
	v_mul_f32_e32 v14, v65, v14
	v_mul_f32_e32 v15, v64, v15
	v_mul_f32_e32 v16, v65, v16
	v_mul_f32_e32 v17, v64, v17
	v_mul_f32_e32 v18, v65, v18
	v_mul_f32_e32 v19, v64, v19
	v_mul_f32_e32 v20, v65, v20
	v_mul_f32_e32 v21, v64, v21
	v_mul_f32_e32 v22, v65, v22
	v_mul_f32_e32 v23, v64, v23
	v_mul_f32_e32 v24, v65, v24
	v_mul_f32_e32 v25, v64, v25
	v_mul_f32_e32 v26, v65, v26
	v_mul_f32_e32 v27, v64, v27
	v_mul_f32_e32 v28, v65, v28
	v_mul_f32_e32 v29, v64, v29
	v_mul_f32_e32 v30, v65, v30
	v_mul_f32_e32 v31, v64, v31
	v_mul_f32_e32 v32, v65, v32
	v_mul_f32_e32 v33, v64, v33
	v_mul_f32_e32 v34, v65, v34
	v_mul_f32_e32 v35, v64, v35
	v_mul_f32_e32 v36, v65, v36
	v_mul_f32_e32 v37, v64, v37
	v_lshlrev_b32_e32 v50, 16, v202
	v_and_b32_e32 v57, 0xffff0000, v202
	v_mul_f32_e32 v51, 0xbfb8aa3b, v50
	v_mul_f32_e32 v58, 0xbfb8aa3b, v57
	v_exp_f32_e32 v51, v51
	v_exp_f32_e32 v58, v58
	v_add_f32_e32 v51, 1.0, v51
	v_add_f32_e32 v58, 1.0, v58
	v_div_scale_f32 v52, s[8:9], v51, v51, v50
	v_div_scale_f32 v59, s[8:9], v58, v58, v57
	v_rcp_f32_e32 v53, v52
	v_rcp_f32_e32 v60, v59
	v_fma_f32 v54, -v52, v53, 1.0
	v_fma_f32 v61, -v59, v60, 1.0
	v_fmac_f32_e32 v53, v54, v53
	v_fmac_f32_e32 v60, v61, v60
	v_div_scale_f32 v55, vcc, v50, v51, v50
	v_mul_f32_e32 v56, v55, v53
	v_fma_f32 v54, -v52, v56, v55
	v_fmac_f32_e32 v56, v54, v53
	v_fma_f32 v52, -v52, v56, v55
	v_div_fmas_f32 v52, v52, v53, v56
	v_div_fixup_f32 v52, v52, v51, v50
	v_mul_f32_e32 v7, v7, v52
	v_div_scale_f32 v62, vcc, v57, v58, v57
	v_mul_f32_e32 v63, v62, v60
	v_fma_f32 v61, -v59, v63, v62
	v_fmac_f32_e32 v63, v61, v60
	v_fma_f32 v59, -v59, v63, v62
	v_div_fmas_f32 v59, v59, v60, v63
	v_div_fixup_f32 v59, v59, v58, v57
	v_mul_f32_e32 v9, v9, v59
	v_cvt_pk_bf16_f32 v194, v7, v9
	v_lshlrev_b32_e32 v50, 16, v203
	v_and_b32_e32 v57, 0xffff0000, v203
	v_mul_f32_e32 v51, 0xbfb8aa3b, v50
	v_mul_f32_e32 v58, 0xbfb8aa3b, v57
	v_exp_f32_e32 v51, v51
	v_exp_f32_e32 v58, v58
	v_add_f32_e32 v51, 1.0, v51
	v_add_f32_e32 v58, 1.0, v58
	v_div_scale_f32 v52, s[8:9], v51, v51, v50
	v_div_scale_f32 v59, s[8:9], v58, v58, v57
	v_rcp_f32_e32 v53, v52
	v_rcp_f32_e32 v60, v59
	v_fma_f32 v54, -v52, v53, 1.0
	v_fma_f32 v61, -v59, v60, 1.0
	v_fmac_f32_e32 v53, v54, v53
	v_fmac_f32_e32 v60, v61, v60
	v_div_scale_f32 v55, vcc, v50, v51, v50
	v_mul_f32_e32 v56, v55, v53
	v_fma_f32 v54, -v52, v56, v55
	v_fmac_f32_e32 v56, v54, v53
	v_fma_f32 v52, -v52, v56, v55
	v_div_fmas_f32 v52, v52, v53, v56
	v_div_fixup_f32 v52, v52, v51, v50
	v_mul_f32_e32 v11, v11, v52
	v_div_scale_f32 v62, vcc, v57, v58, v57
	v_mul_f32_e32 v63, v62, v60
	v_fma_f32 v61, -v59, v63, v62
	v_fmac_f32_e32 v63, v61, v60
	v_fma_f32 v59, -v59, v63, v62
	v_div_fmas_f32 v59, v59, v60, v63
	v_div_fixup_f32 v59, v59, v58, v57
	v_mul_f32_e32 v13, v13, v59
	v_cvt_pk_bf16_f32 v195, v11, v13
	v_lshlrev_b32_e32 v50, 16, v204
	v_and_b32_e32 v57, 0xffff0000, v204
	v_mul_f32_e32 v51, 0xbfb8aa3b, v50
	v_mul_f32_e32 v58, 0xbfb8aa3b, v57
	v_exp_f32_e32 v51, v51
	v_exp_f32_e32 v58, v58
	v_add_f32_e32 v51, 1.0, v51
	v_add_f32_e32 v58, 1.0, v58
	v_div_scale_f32 v52, s[8:9], v51, v51, v50
	v_div_scale_f32 v59, s[8:9], v58, v58, v57
	v_rcp_f32_e32 v53, v52
	v_rcp_f32_e32 v60, v59
	v_fma_f32 v54, -v52, v53, 1.0
	v_fma_f32 v61, -v59, v60, 1.0
	v_fmac_f32_e32 v53, v54, v53
	v_fmac_f32_e32 v60, v61, v60
	v_div_scale_f32 v55, vcc, v50, v51, v50
	v_mul_f32_e32 v56, v55, v53
	v_fma_f32 v54, -v52, v56, v55
	v_fmac_f32_e32 v56, v54, v53
	v_fma_f32 v52, -v52, v56, v55
	v_div_fmas_f32 v52, v52, v53, v56
	v_div_fixup_f32 v52, v52, v51, v50
	v_mul_f32_e32 v15, v15, v52
	v_div_scale_f32 v62, vcc, v57, v58, v57
	v_mul_f32_e32 v63, v62, v60
	v_fma_f32 v61, -v59, v63, v62
	v_fmac_f32_e32 v63, v61, v60
	v_fma_f32 v59, -v59, v63, v62
	v_div_fmas_f32 v59, v59, v60, v63
	v_div_fixup_f32 v59, v59, v58, v57
	v_mul_f32_e32 v17, v17, v59
	v_cvt_pk_bf16_f32 v196, v15, v17
	v_lshlrev_b32_e32 v50, 16, v205
	v_and_b32_e32 v57, 0xffff0000, v205
	v_mul_f32_e32 v51, 0xbfb8aa3b, v50
	v_mul_f32_e32 v58, 0xbfb8aa3b, v57
	v_exp_f32_e32 v51, v51
	v_exp_f32_e32 v58, v58
	v_add_f32_e32 v51, 1.0, v51
	v_add_f32_e32 v58, 1.0, v58
	v_div_scale_f32 v52, s[8:9], v51, v51, v50
	v_div_scale_f32 v59, s[8:9], v58, v58, v57
	v_rcp_f32_e32 v53, v52
	v_rcp_f32_e32 v60, v59
	v_fma_f32 v54, -v52, v53, 1.0
	v_fma_f32 v61, -v59, v60, 1.0
	v_fmac_f32_e32 v53, v54, v53
	v_fmac_f32_e32 v60, v61, v60
	v_div_scale_f32 v55, vcc, v50, v51, v50
	v_mul_f32_e32 v56, v55, v53
	v_fma_f32 v54, -v52, v56, v55
	v_fmac_f32_e32 v56, v54, v53
	v_fma_f32 v52, -v52, v56, v55
	v_div_fmas_f32 v52, v52, v53, v56
	v_div_fixup_f32 v52, v52, v51, v50
	v_mul_f32_e32 v19, v19, v52
	v_div_scale_f32 v62, vcc, v57, v58, v57
	v_mul_f32_e32 v63, v62, v60
	v_fma_f32 v61, -v59, v63, v62
	v_fmac_f32_e32 v63, v61, v60
	v_fma_f32 v59, -v59, v63, v62
	v_div_fmas_f32 v59, v59, v60, v63
	v_div_fixup_f32 v59, v59, v58, v57
	v_mul_f32_e32 v21, v21, v59
	v_cvt_pk_bf16_f32 v197, v19, v21
	v_lshlrev_b32_e32 v50, 16, v210
	v_and_b32_e32 v57, 0xffff0000, v210
	v_mul_f32_e32 v51, 0xbfb8aa3b, v50
	v_mul_f32_e32 v58, 0xbfb8aa3b, v57
	v_exp_f32_e32 v51, v51
	v_exp_f32_e32 v58, v58
	v_add_f32_e32 v51, 1.0, v51
	v_add_f32_e32 v58, 1.0, v58
	v_div_scale_f32 v52, s[8:9], v51, v51, v50
	v_div_scale_f32 v59, s[8:9], v58, v58, v57
	v_rcp_f32_e32 v53, v52
	v_rcp_f32_e32 v60, v59
	v_fma_f32 v54, -v52, v53, 1.0
	v_fma_f32 v61, -v59, v60, 1.0
	v_fmac_f32_e32 v53, v54, v53
	v_fmac_f32_e32 v60, v61, v60
	v_div_scale_f32 v55, vcc, v50, v51, v50
	v_mul_f32_e32 v56, v55, v53
	v_fma_f32 v54, -v52, v56, v55
	v_fmac_f32_e32 v56, v54, v53
	v_fma_f32 v52, -v52, v56, v55
	v_div_fmas_f32 v52, v52, v53, v56
	v_div_fixup_f32 v52, v52, v51, v50
	v_mul_f32_e32 v6, v6, v52
	v_div_scale_f32 v62, vcc, v57, v58, v57
	v_mul_f32_e32 v63, v62, v60
	v_fma_f32 v61, -v59, v63, v62
	v_fmac_f32_e32 v63, v61, v60
	v_fma_f32 v59, -v59, v63, v62
	v_div_fmas_f32 v59, v59, v60, v63
	v_div_fixup_f32 v59, v59, v58, v57
	v_mul_f32_e32 v8, v8, v59
	v_cvt_pk_bf16_f32 v202, v6, v8
	v_lshlrev_b32_e32 v50, 16, v211
	v_and_b32_e32 v57, 0xffff0000, v211
	v_mul_f32_e32 v51, 0xbfb8aa3b, v50
	v_mul_f32_e32 v58, 0xbfb8aa3b, v57
	v_exp_f32_e32 v51, v51
	v_exp_f32_e32 v58, v58
	v_add_f32_e32 v51, 1.0, v51
	v_add_f32_e32 v58, 1.0, v58
	v_div_scale_f32 v52, s[8:9], v51, v51, v50
	v_div_scale_f32 v59, s[8:9], v58, v58, v57
	v_rcp_f32_e32 v53, v52
	v_rcp_f32_e32 v60, v59
	v_fma_f32 v54, -v52, v53, 1.0
	v_fma_f32 v61, -v59, v60, 1.0
	v_fmac_f32_e32 v53, v54, v53
	v_fmac_f32_e32 v60, v61, v60
	v_div_scale_f32 v55, vcc, v50, v51, v50
	v_mul_f32_e32 v56, v55, v53
	v_fma_f32 v54, -v52, v56, v55
	v_fmac_f32_e32 v56, v54, v53
	v_fma_f32 v52, -v52, v56, v55
	v_div_fmas_f32 v52, v52, v53, v56
	v_div_fixup_f32 v52, v52, v51, v50
	v_mul_f32_e32 v10, v10, v52
	v_div_scale_f32 v62, vcc, v57, v58, v57
	v_mul_f32_e32 v63, v62, v60
	v_fma_f32 v61, -v59, v63, v62
	v_fmac_f32_e32 v63, v61, v60
	v_fma_f32 v59, -v59, v63, v62
	v_div_fmas_f32 v59, v59, v60, v63
	v_div_fixup_f32 v59, v59, v58, v57
	v_mul_f32_e32 v12, v12, v59
	v_cvt_pk_bf16_f32 v203, v10, v12
	v_lshlrev_b32_e32 v50, 16, v212
	v_and_b32_e32 v57, 0xffff0000, v212
	v_mul_f32_e32 v51, 0xbfb8aa3b, v50
	v_mul_f32_e32 v58, 0xbfb8aa3b, v57
	v_exp_f32_e32 v51, v51
	v_exp_f32_e32 v58, v58
	v_add_f32_e32 v51, 1.0, v51
	v_add_f32_e32 v58, 1.0, v58
	v_div_scale_f32 v52, s[8:9], v51, v51, v50
	v_div_scale_f32 v59, s[8:9], v58, v58, v57
	v_rcp_f32_e32 v53, v52
	v_rcp_f32_e32 v60, v59
	v_fma_f32 v54, -v52, v53, 1.0
	v_fma_f32 v61, -v59, v60, 1.0
	v_fmac_f32_e32 v53, v54, v53
	v_fmac_f32_e32 v60, v61, v60
	v_div_scale_f32 v55, vcc, v50, v51, v50
	v_mul_f32_e32 v56, v55, v53
	v_fma_f32 v54, -v52, v56, v55
	v_fmac_f32_e32 v56, v54, v53
	v_fma_f32 v52, -v52, v56, v55
	v_div_fmas_f32 v52, v52, v53, v56
	v_div_fixup_f32 v52, v52, v51, v50
	v_mul_f32_e32 v14, v14, v52
	v_div_scale_f32 v62, vcc, v57, v58, v57
	v_mul_f32_e32 v63, v62, v60
	v_fma_f32 v61, -v59, v63, v62
	v_fmac_f32_e32 v63, v61, v60
	v_fma_f32 v59, -v59, v63, v62
	v_div_fmas_f32 v59, v59, v60, v63
	v_div_fixup_f32 v59, v59, v58, v57
	v_mul_f32_e32 v16, v16, v59
	v_cvt_pk_bf16_f32 v204, v14, v16
	v_lshlrev_b32_e32 v50, 16, v213
	v_and_b32_e32 v57, 0xffff0000, v213
	v_mul_f32_e32 v51, 0xbfb8aa3b, v50
	v_mul_f32_e32 v58, 0xbfb8aa3b, v57
	v_exp_f32_e32 v51, v51
	v_exp_f32_e32 v58, v58
	v_add_f32_e32 v51, 1.0, v51
	v_add_f32_e32 v58, 1.0, v58
	v_div_scale_f32 v52, s[8:9], v51, v51, v50
	v_div_scale_f32 v59, s[8:9], v58, v58, v57
	v_rcp_f32_e32 v53, v52
	v_rcp_f32_e32 v60, v59
	v_fma_f32 v54, -v52, v53, 1.0
	v_fma_f32 v61, -v59, v60, 1.0
	v_fmac_f32_e32 v53, v54, v53
	v_fmac_f32_e32 v60, v61, v60
	v_div_scale_f32 v55, vcc, v50, v51, v50
	v_mul_f32_e32 v56, v55, v53
	v_fma_f32 v54, -v52, v56, v55
	v_fmac_f32_e32 v56, v54, v53
	v_fma_f32 v52, -v52, v56, v55
	v_div_fmas_f32 v52, v52, v53, v56
	v_div_fixup_f32 v52, v52, v51, v50
	v_mul_f32_e32 v18, v18, v52
	v_div_scale_f32 v62, vcc, v57, v58, v57
	v_mul_f32_e32 v63, v62, v60
	v_fma_f32 v61, -v59, v63, v62
	v_fmac_f32_e32 v63, v61, v60
	v_fma_f32 v59, -v59, v63, v62
	v_div_fmas_f32 v59, v59, v60, v63
	v_div_fixup_f32 v59, v59, v58, v57
	v_mul_f32_e32 v20, v20, v59
	v_cvt_pk_bf16_f32 v205, v18, v20
	global_store_dwordx4 v[250:251], v[194:197], off
	global_store_dwordx4 v[250:251], v[202:205], off offset:2048
	v_lshlrev_b32_e32 v50, 16, v206
	v_and_b32_e32 v57, 0xffff0000, v206
	v_mul_f32_e32 v51, 0xbfb8aa3b, v50
	v_mul_f32_e32 v58, 0xbfb8aa3b, v57
	v_exp_f32_e32 v51, v51
	v_exp_f32_e32 v58, v58
	v_add_f32_e32 v51, 1.0, v51
	v_add_f32_e32 v58, 1.0, v58
	v_div_scale_f32 v52, s[8:9], v51, v51, v50
	v_div_scale_f32 v59, s[8:9], v58, v58, v57
	v_rcp_f32_e32 v53, v52
	v_rcp_f32_e32 v60, v59
	v_fma_f32 v54, -v52, v53, 1.0
	v_fma_f32 v61, -v59, v60, 1.0
	v_fmac_f32_e32 v53, v54, v53
	v_fmac_f32_e32 v60, v61, v60
	v_div_scale_f32 v55, vcc, v50, v51, v50
	v_mul_f32_e32 v56, v55, v53
	v_fma_f32 v54, -v52, v56, v55
	v_fmac_f32_e32 v56, v54, v53
	v_fma_f32 v52, -v52, v56, v55
	v_div_fmas_f32 v52, v52, v53, v56
	v_div_fixup_f32 v52, v52, v51, v50
	v_mul_f32_e32 v23, v23, v52
	v_div_scale_f32 v62, vcc, v57, v58, v57
	v_mul_f32_e32 v63, v62, v60
	v_fma_f32 v61, -v59, v63, v62
	v_fmac_f32_e32 v63, v61, v60
	v_fma_f32 v59, -v59, v63, v62
	v_div_fmas_f32 v59, v59, v60, v63
	v_div_fixup_f32 v59, v59, v58, v57
	v_mul_f32_e32 v25, v25, v59
	v_cvt_pk_bf16_f32 v198, v23, v25
	v_lshlrev_b32_e32 v50, 16, v207
	v_and_b32_e32 v57, 0xffff0000, v207
	v_mul_f32_e32 v51, 0xbfb8aa3b, v50
	v_mul_f32_e32 v58, 0xbfb8aa3b, v57
	v_exp_f32_e32 v51, v51
	v_exp_f32_e32 v58, v58
	v_add_f32_e32 v51, 1.0, v51
	v_add_f32_e32 v58, 1.0, v58
	v_div_scale_f32 v52, s[8:9], v51, v51, v50
	v_div_scale_f32 v59, s[8:9], v58, v58, v57
	v_rcp_f32_e32 v53, v52
	v_rcp_f32_e32 v60, v59
	v_fma_f32 v54, -v52, v53, 1.0
	v_fma_f32 v61, -v59, v60, 1.0
	v_fmac_f32_e32 v53, v54, v53
	v_fmac_f32_e32 v60, v61, v60
	v_div_scale_f32 v55, vcc, v50, v51, v50
	v_mul_f32_e32 v56, v55, v53
	v_fma_f32 v54, -v52, v56, v55
	v_fmac_f32_e32 v56, v54, v53
	v_fma_f32 v52, -v52, v56, v55
	v_div_fmas_f32 v52, v52, v53, v56
	v_div_fixup_f32 v52, v52, v51, v50
	v_mul_f32_e32 v27, v27, v52
	v_div_scale_f32 v62, vcc, v57, v58, v57
	v_mul_f32_e32 v63, v62, v60
	v_fma_f32 v61, -v59, v63, v62
	v_fmac_f32_e32 v63, v61, v60
	v_fma_f32 v59, -v59, v63, v62
	v_div_fmas_f32 v59, v59, v60, v63
	v_div_fixup_f32 v59, v59, v58, v57
	v_mul_f32_e32 v29, v29, v59
	v_cvt_pk_bf16_f32 v199, v27, v29
	v_lshlrev_b32_e32 v50, 16, v208
	v_and_b32_e32 v57, 0xffff0000, v208
	v_mul_f32_e32 v51, 0xbfb8aa3b, v50
	v_mul_f32_e32 v58, 0xbfb8aa3b, v57
	v_exp_f32_e32 v51, v51
	v_exp_f32_e32 v58, v58
	v_add_f32_e32 v51, 1.0, v51
	v_add_f32_e32 v58, 1.0, v58
	v_div_scale_f32 v52, s[8:9], v51, v51, v50
	v_div_scale_f32 v59, s[8:9], v58, v58, v57
	v_rcp_f32_e32 v53, v52
	v_rcp_f32_e32 v60, v59
	v_fma_f32 v54, -v52, v53, 1.0
	v_fma_f32 v61, -v59, v60, 1.0
	v_fmac_f32_e32 v53, v54, v53
	v_fmac_f32_e32 v60, v61, v60
	v_div_scale_f32 v55, vcc, v50, v51, v50
	v_mul_f32_e32 v56, v55, v53
	v_fma_f32 v54, -v52, v56, v55
	v_fmac_f32_e32 v56, v54, v53
	v_fma_f32 v52, -v52, v56, v55
	v_div_fmas_f32 v52, v52, v53, v56
	v_div_fixup_f32 v52, v52, v51, v50
	v_mul_f32_e32 v31, v31, v52
	v_div_scale_f32 v62, vcc, v57, v58, v57
	v_mul_f32_e32 v63, v62, v60
	v_fma_f32 v61, -v59, v63, v62
	v_fmac_f32_e32 v63, v61, v60
	v_fma_f32 v59, -v59, v63, v62
	v_div_fmas_f32 v59, v59, v60, v63
	v_div_fixup_f32 v59, v59, v58, v57
	v_mul_f32_e32 v33, v33, v59
	v_cvt_pk_bf16_f32 v200, v31, v33
	v_lshlrev_b32_e32 v50, 16, v209
	v_and_b32_e32 v57, 0xffff0000, v209
	v_mul_f32_e32 v51, 0xbfb8aa3b, v50
	v_mul_f32_e32 v58, 0xbfb8aa3b, v57
	v_exp_f32_e32 v51, v51
	v_exp_f32_e32 v58, v58
	v_add_f32_e32 v51, 1.0, v51
	v_add_f32_e32 v58, 1.0, v58
	v_div_scale_f32 v52, s[8:9], v51, v51, v50
	v_div_scale_f32 v59, s[8:9], v58, v58, v57
	v_rcp_f32_e32 v53, v52
	v_rcp_f32_e32 v60, v59
	v_fma_f32 v54, -v52, v53, 1.0
	v_fma_f32 v61, -v59, v60, 1.0
	v_fmac_f32_e32 v53, v54, v53
	v_fmac_f32_e32 v60, v61, v60
	v_div_scale_f32 v55, vcc, v50, v51, v50
	v_mul_f32_e32 v56, v55, v53
	v_fma_f32 v54, -v52, v56, v55
	v_fmac_f32_e32 v56, v54, v53
	v_fma_f32 v52, -v52, v56, v55
	v_div_fmas_f32 v52, v52, v53, v56
	v_div_fixup_f32 v52, v52, v51, v50
	v_mul_f32_e32 v35, v35, v52
	v_div_scale_f32 v62, vcc, v57, v58, v57
	v_mul_f32_e32 v63, v62, v60
	v_fma_f32 v61, -v59, v63, v62
	v_fmac_f32_e32 v63, v61, v60
	v_fma_f32 v59, -v59, v63, v62
	v_div_fmas_f32 v59, v59, v60, v63
	v_div_fixup_f32 v59, v59, v58, v57
	v_mul_f32_e32 v37, v37, v59
	v_cvt_pk_bf16_f32 v201, v35, v37
	v_lshlrev_b32_e32 v50, 16, v214
	v_and_b32_e32 v57, 0xffff0000, v214
	v_mul_f32_e32 v51, 0xbfb8aa3b, v50
	v_mul_f32_e32 v58, 0xbfb8aa3b, v57
	v_exp_f32_e32 v51, v51
	v_exp_f32_e32 v58, v58
	v_add_f32_e32 v51, 1.0, v51
	v_add_f32_e32 v58, 1.0, v58
	v_div_scale_f32 v52, s[8:9], v51, v51, v50
	v_div_scale_f32 v59, s[8:9], v58, v58, v57
	v_rcp_f32_e32 v53, v52
	v_rcp_f32_e32 v60, v59
	v_fma_f32 v54, -v52, v53, 1.0
	v_fma_f32 v61, -v59, v60, 1.0
	v_fmac_f32_e32 v53, v54, v53
	v_fmac_f32_e32 v60, v61, v60
	v_div_scale_f32 v55, vcc, v50, v51, v50
	v_mul_f32_e32 v56, v55, v53
	v_fma_f32 v54, -v52, v56, v55
	v_fmac_f32_e32 v56, v54, v53
	v_fma_f32 v52, -v52, v56, v55
	v_div_fmas_f32 v52, v52, v53, v56
	v_div_fixup_f32 v52, v52, v51, v50
	v_mul_f32_e32 v22, v22, v52
	v_div_scale_f32 v62, vcc, v57, v58, v57
	v_mul_f32_e32 v63, v62, v60
	v_fma_f32 v61, -v59, v63, v62
	v_fmac_f32_e32 v63, v61, v60
	v_fma_f32 v59, -v59, v63, v62
	v_div_fmas_f32 v59, v59, v60, v63
	v_div_fixup_f32 v59, v59, v58, v57
	v_mul_f32_e32 v24, v24, v59
	v_cvt_pk_bf16_f32 v206, v22, v24
	v_lshlrev_b32_e32 v50, 16, v215
	v_and_b32_e32 v57, 0xffff0000, v215
	v_mul_f32_e32 v51, 0xbfb8aa3b, v50
	v_mul_f32_e32 v58, 0xbfb8aa3b, v57
	v_exp_f32_e32 v51, v51
	v_exp_f32_e32 v58, v58
	v_add_f32_e32 v51, 1.0, v51
	v_add_f32_e32 v58, 1.0, v58
	v_div_scale_f32 v52, s[8:9], v51, v51, v50
	v_div_scale_f32 v59, s[8:9], v58, v58, v57
	v_rcp_f32_e32 v53, v52
	v_rcp_f32_e32 v60, v59
	v_fma_f32 v54, -v52, v53, 1.0
	v_fma_f32 v61, -v59, v60, 1.0
	v_fmac_f32_e32 v53, v54, v53
	v_fmac_f32_e32 v60, v61, v60
	v_div_scale_f32 v55, vcc, v50, v51, v50
	v_mul_f32_e32 v56, v55, v53
	v_fma_f32 v54, -v52, v56, v55
	v_fmac_f32_e32 v56, v54, v53
	v_fma_f32 v52, -v52, v56, v55
	v_div_fmas_f32 v52, v52, v53, v56
	v_div_fixup_f32 v52, v52, v51, v50
	v_mul_f32_e32 v26, v26, v52
	v_div_scale_f32 v62, vcc, v57, v58, v57
	v_mul_f32_e32 v63, v62, v60
	v_fma_f32 v61, -v59, v63, v62
	v_fmac_f32_e32 v63, v61, v60
	v_fma_f32 v59, -v59, v63, v62
	v_div_fmas_f32 v59, v59, v60, v63
	v_div_fixup_f32 v59, v59, v58, v57
	v_mul_f32_e32 v28, v28, v59
	v_cvt_pk_bf16_f32 v207, v26, v28
	v_lshlrev_b32_e32 v50, 16, v216
	v_and_b32_e32 v57, 0xffff0000, v216
	v_mul_f32_e32 v51, 0xbfb8aa3b, v50
	v_mul_f32_e32 v58, 0xbfb8aa3b, v57
	v_exp_f32_e32 v51, v51
	v_exp_f32_e32 v58, v58
	v_add_f32_e32 v51, 1.0, v51
	v_add_f32_e32 v58, 1.0, v58
	v_div_scale_f32 v52, s[8:9], v51, v51, v50
	v_div_scale_f32 v59, s[8:9], v58, v58, v57
	v_rcp_f32_e32 v53, v52
	v_rcp_f32_e32 v60, v59
	v_fma_f32 v54, -v52, v53, 1.0
	v_fma_f32 v61, -v59, v60, 1.0
	v_fmac_f32_e32 v53, v54, v53
	v_fmac_f32_e32 v60, v61, v60
	v_div_scale_f32 v55, vcc, v50, v51, v50
	v_mul_f32_e32 v56, v55, v53
	v_fma_f32 v54, -v52, v56, v55
	v_fmac_f32_e32 v56, v54, v53
	v_fma_f32 v52, -v52, v56, v55
	v_div_fmas_f32 v52, v52, v53, v56
	v_div_fixup_f32 v52, v52, v51, v50
	v_mul_f32_e32 v30, v30, v52
	v_div_scale_f32 v62, vcc, v57, v58, v57
	v_mul_f32_e32 v63, v62, v60
	v_fma_f32 v61, -v59, v63, v62
	v_fmac_f32_e32 v63, v61, v60
	v_fma_f32 v59, -v59, v63, v62
	v_div_fmas_f32 v59, v59, v60, v63
	v_div_fixup_f32 v59, v59, v58, v57
	v_mul_f32_e32 v32, v32, v59
	v_cvt_pk_bf16_f32 v208, v30, v32
	v_lshlrev_b32_e32 v50, 16, v217
	v_and_b32_e32 v57, 0xffff0000, v217
	v_mul_f32_e32 v51, 0xbfb8aa3b, v50
	v_mul_f32_e32 v58, 0xbfb8aa3b, v57
	v_exp_f32_e32 v51, v51
	v_exp_f32_e32 v58, v58
	v_add_f32_e32 v51, 1.0, v51
	v_add_f32_e32 v58, 1.0, v58
	v_div_scale_f32 v52, s[8:9], v51, v51, v50
	v_div_scale_f32 v59, s[8:9], v58, v58, v57
	v_rcp_f32_e32 v53, v52
	v_rcp_f32_e32 v60, v59
	v_fma_f32 v54, -v52, v53, 1.0
	v_fma_f32 v61, -v59, v60, 1.0
	v_fmac_f32_e32 v53, v54, v53
	v_fmac_f32_e32 v60, v61, v60
	v_div_scale_f32 v55, vcc, v50, v51, v50
	v_mul_f32_e32 v56, v55, v53
	v_fma_f32 v54, -v52, v56, v55
	v_fmac_f32_e32 v56, v54, v53
	v_fma_f32 v52, -v52, v56, v55
	v_div_fmas_f32 v52, v52, v53, v56
	v_div_fixup_f32 v52, v52, v51, v50
	v_mul_f32_e32 v34, v34, v52
	v_div_scale_f32 v62, vcc, v57, v58, v57
	v_mul_f32_e32 v63, v62, v60
	v_fma_f32 v61, -v59, v63, v62
	v_fmac_f32_e32 v63, v61, v60
	v_fma_f32 v59, -v59, v63, v62
	v_div_fmas_f32 v59, v59, v60, v63
	v_div_fixup_f32 v59, v59, v58, v57
	v_mul_f32_e32 v36, v36, v59
	v_cvt_pk_bf16_f32 v209, v34, v36
	global_store_dwordx4 v[250:251], v[198:201], off offset:1024
	global_store_dwordx4 v[250:251], v[206:209], off offset:3072
	s_addk_i32 s0, 0x810
	s_cmpk_eq_i32 s0, 0x3870
	s_cbranch_scc1 .Lmg_nopf
	global_load_dwordx4 v[194:197], v[2:3], off
	global_load_dwordx4 v[198:201], v[2:3], off offset:1024
	global_load_dwordx4 v[202:205], v[0:1], off offset:1664
	global_load_dwordx4 v[206:209], v[0:1], off offset:2688
	global_load_dwordx4 v[210:213], v[0:1], off offset:3712
	v_lshl_add_u64 v[4:5], v[0:1], 0, s[10:11]
	global_load_dwordx4 v[214:217], v[4:5], off offset:2688
	v_mov_b32_e32 v250, v2
	v_mov_b32_e32 v251, v3
	s_mov_b64 s[8:9], 0x1000
	v_lshl_add_u64 v[2:3], v[2:3], 0, s[8:9]
	s_mov_b64 s[8:9], 0x1700
	v_lshl_add_u64 v[0:1], v[0:1], 0, s[8:9]
	v_add_u32_e32 v66, s0, v46
	ds_read_b128 v[242:245], v66
	ds_read_b128 v[246:249], v66 offset:1024
	s_waitcnt vmcnt(6)
	s_branch .Lmg_go
.Lmg_nopf:
	v_add_u32_e32 v66, s0, v46
	ds_read_b128 v[242:245], v66
	ds_read_b128 v[246:249], v66 offset:1024
	s_waitcnt vmcnt(0)
.Lmg_go:
	s_waitcnt lgkmcnt(0)
	v_lshlrev_b32_e32 v6, 16, v242
	v_lshlrev_b32_e32 v7, 16, v218
	v_and_b32_e32 v8, 0xffff0000, v242
	v_and_b32_e32 v9, 0xffff0000, v218
	v_lshlrev_b32_e32 v10, 16, v243
	v_lshlrev_b32_e32 v11, 16, v219
	v_and_b32_e32 v12, 0xffff0000, v243
	v_and_b32_e32 v13, 0xffff0000, v219
	v_lshlrev_b32_e32 v14, 16, v244
	v_lshlrev_b32_e32 v15, 16, v220
	v_and_b32_e32 v16, 0xffff0000, v244
	v_and_b32_e32 v17, 0xffff0000, v220
	v_lshlrev_b32_e32 v18, 16, v245
	v_lshlrev_b32_e32 v19, 16, v221
	v_and_b32_e32 v20, 0xffff0000, v245
	v_and_b32_e32 v21, 0xffff0000, v221
	v_lshlrev_b32_e32 v22, 16, v246
	v_lshlrev_b32_e32 v23, 16, v222
	v_and_b32_e32 v24, 0xffff0000, v246
	v_and_b32_e32 v25, 0xffff0000, v222
	v_lshlrev_b32_e32 v26, 16, v247
	v_lshlrev_b32_e32 v27, 16, v223
	v_and_b32_e32 v28, 0xffff0000, v247
	v_and_b32_e32 v29, 0xffff0000, v223
	v_lshlrev_b32_e32 v30, 16, v248
	v_lshlrev_b32_e32 v31, 16, v224
	v_and_b32_e32 v32, 0xffff0000, v248
	v_and_b32_e32 v33, 0xffff0000, v224
	v_lshlrev_b32_e32 v34, 16, v249
	v_lshlrev_b32_e32 v35, 16, v225
	v_and_b32_e32 v36, 0xffff0000, v249
	v_and_b32_e32 v37, 0xffff0000, v225
	v_pk_mul_f32 v[38:39], v[8:9], v[8:9]
	v_pk_fma_f32 v[38:39], v[6:7], v[6:7], v[38:39]
	v_pk_fma_f32 v[38:39], v[10:11], v[10:11], v[38:39]
	v_pk_fma_f32 v[38:39], v[12:13], v[12:13], v[38:39]
	v_pk_fma_f32 v[38:39], v[14:15], v[14:15], v[38:39]
	v_pk_fma_f32 v[38:39], v[16:17], v[16:17], v[38:39]
	v_pk_fma_f32 v[38:39], v[18:19], v[18:19], v[38:39]
	v_pk_fma_f32 v[38:39], v[20:21], v[20:21], v[38:39]
	v_pk_fma_f32 v[38:39], v[22:23], v[22:23], v[38:39]
	v_pk_fma_f32 v[38:39], v[24:25], v[24:25], v[38:39]
	v_pk_fma_f32 v[38:39], v[26:27], v[26:27], v[38:39]
	v_pk_fma_f32 v[38:39], v[28:29], v[28:29], v[38:39]
	v_pk_mul_f32 v[48:49], v[30:31], v[30:31]
	v_pk_add_f32 v[38:39], v[48:49], v[38:39]
	v_pk_mul_f32 v[48:49], v[32:33], v[32:33]
	v_pk_add_f32 v[38:39], v[48:49], v[38:39]
	v_pk_mul_f32 v[48:49], v[34:35], v[34:35]
	v_pk_add_f32 v[38:39], v[48:49], v[38:39]
	v_pk_mul_f32 v[48:49], v[36:37], v[36:37]
	v_pk_add_f32 v[38:39], v[48:49], v[38:39]
	v_mov_b32_e32 v48, v38
	v_mov_b32_e32 v49, v39
	s_nop 1
	v_permlane32_swap_b32_e32 v38, v48
	v_permlane32_swap_b32_e32 v39, v49
	s_nop 0
	v_add_f32_e32 v38, v38, v48
	v_add_f32_e32 v39, v39, v49
	v_mov_b32_e32 v48, v38
	v_mov_b32_e32 v49, v39
	s_nop 1
	v_permlane16_swap_b32_e32 v38, v48
	v_permlane16_swap_b32_e32 v39, v49
	s_nop 0
	v_add_f32_e32 v38, v38, v48
	v_add_f32_e32 v39, v39, v49
	s_nop 1
	v_add_f32_dpp v38, v38, v38 row_ror:8 row_mask:0xf bank_mask:0xf
	v_add_f32_dpp v39, v39, v39 row_ror:8 row_mask:0xf bank_mask:0xf
	s_nop 1
	v_add_f32_dpp v38, v38, v38 row_ror:4 row_mask:0xf bank_mask:0xf
	v_add_f32_dpp v39, v39, v39 row_ror:4 row_mask:0xf bank_mask:0xf
	s_nop 1
	v_add_f32_dpp v38, v38, v38 row_ror:2 row_mask:0xf bank_mask:0xf
	v_add_f32_dpp v39, v39, v39 row_ror:2 row_mask:0xf bank_mask:0xf
	s_nop 1
	v_add_f32_dpp v38, v38, v38 row_ror:1 row_mask:0xf bank_mask:0xf
	v_add_f32_dpp v39, v39, v39 row_ror:1 row_mask:0xf bank_mask:0xf
	s_nop 1
	v_pk_fma_f32 v[38:39], v[38:39], s[20:21], v[166:167] op_sel_hi:[1,0,0]
	s_nop 0
	v_mul_f32_e32 v47, 0x4b800000, v39
	v_cmp_gt_f32_e64 s[10:11], s58, v39
	v_cmp_gt_f32_e32 vcc, s58, v38
	s_nop 1
	v_cndmask_b32_e64 v39, v39, v47, s[10:11]
	v_rsq_f32_e32 v39, v39
	s_nop 0
	v_mul_f32_e32 v47, 0x45800000, v39
	v_cndmask_b32_e64 v64, v39, v47, s[10:11]
	v_mul_f32_e32 v39, 0x4b800000, v38
	v_cndmask_b32_e32 v38, v38, v39, vcc
	v_rsq_f32_e32 v38, v38
	s_nop 0
	v_mul_f32_e32 v39, 0x45800000, v38
	v_cndmask_b32_e32 v65, v38, v39, vcc
	s_mov_b64 s[10:11], 0x800
	v_mul_f32_e32 v6, v65, v6
	v_mul_f32_e32 v7, v64, v7
	v_mul_f32_e32 v8, v65, v8
	v_mul_f32_e32 v9, v64, v9
	v_mul_f32_e32 v10, v65, v10
	v_mul_f32_e32 v11, v64, v11
	v_mul_f32_e32 v12, v65, v12
	v_mul_f32_e32 v13, v64, v13
	v_mul_f32_e32 v14, v65, v14
	v_mul_f32_e32 v15, v64, v15
	v_mul_f32_e32 v16, v65, v16
	v_mul_f32_e32 v17, v64, v17
	v_mul_f32_e32 v18, v65, v18
	v_mul_f32_e32 v19, v64, v19
	v_mul_f32_e32 v20, v65, v20
	v_mul_f32_e32 v21, v64, v21
	v_mul_f32_e32 v22, v65, v22
	v_mul_f32_e32 v23, v64, v23
	v_mul_f32_e32 v24, v65, v24
	v_mul_f32_e32 v25, v64, v25
	v_mul_f32_e32 v26, v65, v26
	v_mul_f32_e32 v27, v64, v27
	v_mul_f32_e32 v28, v65, v28
	v_mul_f32_e32 v29, v64, v29
	v_mul_f32_e32 v30, v65, v30
	v_mul_f32_e32 v31, v64, v31
	v_mul_f32_e32 v32, v65, v32
	v_mul_f32_e32 v33, v64, v33
	v_mul_f32_e32 v34, v65, v34
	v_mul_f32_e32 v35, v64, v35
	v_mul_f32_e32 v36, v65, v36
	v_mul_f32_e32 v37, v64, v37
	v_lshlrev_b32_e32 v50, 16, v226
	v_and_b32_e32 v57, 0xffff0000, v226
	v_mul_f32_e32 v51, 0xbfb8aa3b, v50
	v_mul_f32_e32 v58, 0xbfb8aa3b, v57
	v_exp_f32_e32 v51, v51
	v_exp_f32_e32 v58, v58
	v_add_f32_e32 v51, 1.0, v51
	v_add_f32_e32 v58, 1.0, v58
	v_div_scale_f32 v52, s[8:9], v51, v51, v50
	v_div_scale_f32 v59, s[8:9], v58, v58, v57
	v_rcp_f32_e32 v53, v52
	v_rcp_f32_e32 v60, v59
	v_fma_f32 v54, -v52, v53, 1.0
	v_fma_f32 v61, -v59, v60, 1.0
	v_fmac_f32_e32 v53, v54, v53
	v_fmac_f32_e32 v60, v61, v60
	v_div_scale_f32 v55, vcc, v50, v51, v50
	v_mul_f32_e32 v56, v55, v53
	v_fma_f32 v54, -v52, v56, v55
	v_fmac_f32_e32 v56, v54, v53
	v_fma_f32 v52, -v52, v56, v55
	v_div_fmas_f32 v52, v52, v53, v56
	v_div_fixup_f32 v52, v52, v51, v50
	v_mul_f32_e32 v7, v7, v52
	v_div_scale_f32 v62, vcc, v57, v58, v57
	v_mul_f32_e32 v63, v62, v60
	v_fma_f32 v61, -v59, v63, v62
	v_fmac_f32_e32 v63, v61, v60
	v_fma_f32 v59, -v59, v63, v62
	v_div_fmas_f32 v59, v59, v60, v63
	v_div_fixup_f32 v59, v59, v58, v57
	v_mul_f32_e32 v9, v9, v59
	v_cvt_pk_bf16_f32 v218, v7, v9
	v_lshlrev_b32_e32 v50, 16, v227
	v_and_b32_e32 v57, 0xffff0000, v227
	v_mul_f32_e32 v51, 0xbfb8aa3b, v50
	v_mul_f32_e32 v58, 0xbfb8aa3b, v57
	v_exp_f32_e32 v51, v51
	v_exp_f32_e32 v58, v58
	v_add_f32_e32 v51, 1.0, v51
	v_add_f32_e32 v58, 1.0, v58
	v_div_scale_f32 v52, s[8:9], v51, v51, v50
	v_div_scale_f32 v59, s[8:9], v58, v58, v57
	v_rcp_f32_e32 v53, v52
	v_rcp_f32_e32 v60, v59
	v_fma_f32 v54, -v52, v53, 1.0
	v_fma_f32 v61, -v59, v60, 1.0
	v_fmac_f32_e32 v53, v54, v53
	v_fmac_f32_e32 v60, v61, v60
	v_div_scale_f32 v55, vcc, v50, v51, v50
	v_mul_f32_e32 v56, v55, v53
	v_fma_f32 v54, -v52, v56, v55
	v_fmac_f32_e32 v56, v54, v53
	v_fma_f32 v52, -v52, v56, v55
	v_div_fmas_f32 v52, v52, v53, v56
	v_div_fixup_f32 v52, v52, v51, v50
	v_mul_f32_e32 v11, v11, v52
	v_div_scale_f32 v62, vcc, v57, v58, v57
	v_mul_f32_e32 v63, v62, v60
	v_fma_f32 v61, -v59, v63, v62
	v_fmac_f32_e32 v63, v61, v60
	v_fma_f32 v59, -v59, v63, v62
	v_div_fmas_f32 v59, v59, v60, v63
	v_div_fixup_f32 v59, v59, v58, v57
	v_mul_f32_e32 v13, v13, v59
	v_cvt_pk_bf16_f32 v219, v11, v13
	v_lshlrev_b32_e32 v50, 16, v228
	v_and_b32_e32 v57, 0xffff0000, v228
	v_mul_f32_e32 v51, 0xbfb8aa3b, v50
	v_mul_f32_e32 v58, 0xbfb8aa3b, v57
	v_exp_f32_e32 v51, v51
	v_exp_f32_e32 v58, v58
	v_add_f32_e32 v51, 1.0, v51
	v_add_f32_e32 v58, 1.0, v58
	v_div_scale_f32 v52, s[8:9], v51, v51, v50
	v_div_scale_f32 v59, s[8:9], v58, v58, v57
	v_rcp_f32_e32 v53, v52
	v_rcp_f32_e32 v60, v59
	v_fma_f32 v54, -v52, v53, 1.0
	v_fma_f32 v61, -v59, v60, 1.0
	v_fmac_f32_e32 v53, v54, v53
	v_fmac_f32_e32 v60, v61, v60
	v_div_scale_f32 v55, vcc, v50, v51, v50
	v_mul_f32_e32 v56, v55, v53
	v_fma_f32 v54, -v52, v56, v55
	v_fmac_f32_e32 v56, v54, v53
	v_fma_f32 v52, -v52, v56, v55
	v_div_fmas_f32 v52, v52, v53, v56
	v_div_fixup_f32 v52, v52, v51, v50
	v_mul_f32_e32 v15, v15, v52
	v_div_scale_f32 v62, vcc, v57, v58, v57
	v_mul_f32_e32 v63, v62, v60
	v_fma_f32 v61, -v59, v63, v62
	v_fmac_f32_e32 v63, v61, v60
	v_fma_f32 v59, -v59, v63, v62
	v_div_fmas_f32 v59, v59, v60, v63
	v_div_fixup_f32 v59, v59, v58, v57
	v_mul_f32_e32 v17, v17, v59
	v_cvt_pk_bf16_f32 v220, v15, v17
	v_lshlrev_b32_e32 v50, 16, v229
	v_and_b32_e32 v57, 0xffff0000, v229
	v_mul_f32_e32 v51, 0xbfb8aa3b, v50
	v_mul_f32_e32 v58, 0xbfb8aa3b, v57
	v_exp_f32_e32 v51, v51
	v_exp_f32_e32 v58, v58
	v_add_f32_e32 v51, 1.0, v51
	v_add_f32_e32 v58, 1.0, v58
	v_div_scale_f32 v52, s[8:9], v51, v51, v50
	v_div_scale_f32 v59, s[8:9], v58, v58, v57
	v_rcp_f32_e32 v53, v52
	v_rcp_f32_e32 v60, v59
	v_fma_f32 v54, -v52, v53, 1.0
	v_fma_f32 v61, -v59, v60, 1.0
	v_fmac_f32_e32 v53, v54, v53
	v_fmac_f32_e32 v60, v61, v60
	v_div_scale_f32 v55, vcc, v50, v51, v50
	v_mul_f32_e32 v56, v55, v53
	v_fma_f32 v54, -v52, v56, v55
	v_fmac_f32_e32 v56, v54, v53
	v_fma_f32 v52, -v52, v56, v55
	v_div_fmas_f32 v52, v52, v53, v56
	v_div_fixup_f32 v52, v52, v51, v50
	v_mul_f32_e32 v19, v19, v52
	v_div_scale_f32 v62, vcc, v57, v58, v57
	v_mul_f32_e32 v63, v62, v60
	v_fma_f32 v61, -v59, v63, v62
	v_fmac_f32_e32 v63, v61, v60
	v_fma_f32 v59, -v59, v63, v62
	v_div_fmas_f32 v59, v59, v60, v63
	v_div_fixup_f32 v59, v59, v58, v57
	v_mul_f32_e32 v21, v21, v59
	v_cvt_pk_bf16_f32 v221, v19, v21
	v_lshlrev_b32_e32 v50, 16, v234
	v_and_b32_e32 v57, 0xffff0000, v234
	v_mul_f32_e32 v51, 0xbfb8aa3b, v50
	v_mul_f32_e32 v58, 0xbfb8aa3b, v57
	v_exp_f32_e32 v51, v51
	v_exp_f32_e32 v58, v58
	v_add_f32_e32 v51, 1.0, v51
	v_add_f32_e32 v58, 1.0, v58
	v_div_scale_f32 v52, s[8:9], v51, v51, v50
	v_div_scale_f32 v59, s[8:9], v58, v58, v57
	v_rcp_f32_e32 v53, v52
	v_rcp_f32_e32 v60, v59
	v_fma_f32 v54, -v52, v53, 1.0
	v_fma_f32 v61, -v59, v60, 1.0
	v_fmac_f32_e32 v53, v54, v53
	v_fmac_f32_e32 v60, v61, v60
	v_div_scale_f32 v55, vcc, v50, v51, v50
	v_mul_f32_e32 v56, v55, v53
	v_fma_f32 v54, -v52, v56, v55
	v_fmac_f32_e32 v56, v54, v53
	v_fma_f32 v52, -v52, v56, v55
	v_div_fmas_f32 v52, v52, v53, v56
	v_div_fixup_f32 v52, v52, v51, v50
	v_mul_f32_e32 v6, v6, v52
	v_div_scale_f32 v62, vcc, v57, v58, v57
	v_mul_f32_e32 v63, v62, v60
	v_fma_f32 v61, -v59, v63, v62
	v_fmac_f32_e32 v63, v61, v60
	v_fma_f32 v59, -v59, v63, v62
	v_div_fmas_f32 v59, v59, v60, v63
	v_div_fixup_f32 v59, v59, v58, v57
	v_mul_f32_e32 v8, v8, v59
	v_cvt_pk_bf16_f32 v226, v6, v8
	v_lshlrev_b32_e32 v50, 16, v235
	v_and_b32_e32 v57, 0xffff0000, v235
	v_mul_f32_e32 v51, 0xbfb8aa3b, v50
	v_mul_f32_e32 v58, 0xbfb8aa3b, v57
	v_exp_f32_e32 v51, v51
	v_exp_f32_e32 v58, v58
	v_add_f32_e32 v51, 1.0, v51
	v_add_f32_e32 v58, 1.0, v58
	v_div_scale_f32 v52, s[8:9], v51, v51, v50
	v_div_scale_f32 v59, s[8:9], v58, v58, v57
	v_rcp_f32_e32 v53, v52
	v_rcp_f32_e32 v60, v59
	v_fma_f32 v54, -v52, v53, 1.0
	v_fma_f32 v61, -v59, v60, 1.0
	v_fmac_f32_e32 v53, v54, v53
	v_fmac_f32_e32 v60, v61, v60
	v_div_scale_f32 v55, vcc, v50, v51, v50
	v_mul_f32_e32 v56, v55, v53
	v_fma_f32 v54, -v52, v56, v55
	v_fmac_f32_e32 v56, v54, v53
	v_fma_f32 v52, -v52, v56, v55
	v_div_fmas_f32 v52, v52, v53, v56
	v_div_fixup_f32 v52, v52, v51, v50
	v_mul_f32_e32 v10, v10, v52
	v_div_scale_f32 v62, vcc, v57, v58, v57
	v_mul_f32_e32 v63, v62, v60
	v_fma_f32 v61, -v59, v63, v62
	v_fmac_f32_e32 v63, v61, v60
	v_fma_f32 v59, -v59, v63, v62
	v_div_fmas_f32 v59, v59, v60, v63
	v_div_fixup_f32 v59, v59, v58, v57
	v_mul_f32_e32 v12, v12, v59
	v_cvt_pk_bf16_f32 v227, v10, v12
	v_lshlrev_b32_e32 v50, 16, v236
	v_and_b32_e32 v57, 0xffff0000, v236
	v_mul_f32_e32 v51, 0xbfb8aa3b, v50
	v_mul_f32_e32 v58, 0xbfb8aa3b, v57
	v_exp_f32_e32 v51, v51
	v_exp_f32_e32 v58, v58
	v_add_f32_e32 v51, 1.0, v51
	v_add_f32_e32 v58, 1.0, v58
	v_div_scale_f32 v52, s[8:9], v51, v51, v50
	v_div_scale_f32 v59, s[8:9], v58, v58, v57
	v_rcp_f32_e32 v53, v52
	v_rcp_f32_e32 v60, v59
	v_fma_f32 v54, -v52, v53, 1.0
	v_fma_f32 v61, -v59, v60, 1.0
	v_fmac_f32_e32 v53, v54, v53
	v_fmac_f32_e32 v60, v61, v60
	v_div_scale_f32 v55, vcc, v50, v51, v50
	v_mul_f32_e32 v56, v55, v53
	v_fma_f32 v54, -v52, v56, v55
	v_fmac_f32_e32 v56, v54, v53
	v_fma_f32 v52, -v52, v56, v55
	v_div_fmas_f32 v52, v52, v53, v56
	v_div_fixup_f32 v52, v52, v51, v50
	v_mul_f32_e32 v14, v14, v52
	v_div_scale_f32 v62, vcc, v57, v58, v57
	v_mul_f32_e32 v63, v62, v60
	v_fma_f32 v61, -v59, v63, v62
	v_fmac_f32_e32 v63, v61, v60
	v_fma_f32 v59, -v59, v63, v62
	v_div_fmas_f32 v59, v59, v60, v63
	v_div_fixup_f32 v59, v59, v58, v57
	v_mul_f32_e32 v16, v16, v59
	v_cvt_pk_bf16_f32 v228, v14, v16
	v_lshlrev_b32_e32 v50, 16, v237
	v_and_b32_e32 v57, 0xffff0000, v237
	v_mul_f32_e32 v51, 0xbfb8aa3b, v50
	v_mul_f32_e32 v58, 0xbfb8aa3b, v57
	v_exp_f32_e32 v51, v51
	v_exp_f32_e32 v58, v58
	v_add_f32_e32 v51, 1.0, v51
	v_add_f32_e32 v58, 1.0, v58
	v_div_scale_f32 v52, s[8:9], v51, v51, v50
	v_div_scale_f32 v59, s[8:9], v58, v58, v57
	v_rcp_f32_e32 v53, v52
	v_rcp_f32_e32 v60, v59
	v_fma_f32 v54, -v52, v53, 1.0
	v_fma_f32 v61, -v59, v60, 1.0
	v_fmac_f32_e32 v53, v54, v53
	v_fmac_f32_e32 v60, v61, v60
	v_div_scale_f32 v55, vcc, v50, v51, v50
	v_mul_f32_e32 v56, v55, v53
	v_fma_f32 v54, -v52, v56, v55
	v_fmac_f32_e32 v56, v54, v53
	v_fma_f32 v52, -v52, v56, v55
	v_div_fmas_f32 v52, v52, v53, v56
	v_div_fixup_f32 v52, v52, v51, v50
	v_mul_f32_e32 v18, v18, v52
	v_div_scale_f32 v62, vcc, v57, v58, v57
	v_mul_f32_e32 v63, v62, v60
	v_fma_f32 v61, -v59, v63, v62
	v_fmac_f32_e32 v63, v61, v60
	v_fma_f32 v59, -v59, v63, v62
	v_div_fmas_f32 v59, v59, v60, v63
	v_div_fixup_f32 v59, v59, v58, v57
	v_mul_f32_e32 v20, v20, v59
	v_cvt_pk_bf16_f32 v229, v18, v20
	global_store_dwordx4 v[252:253], v[218:221], off
	global_store_dwordx4 v[252:253], v[226:229], off offset:2048
	v_lshlrev_b32_e32 v50, 16, v230
	v_and_b32_e32 v57, 0xffff0000, v230
	v_mul_f32_e32 v51, 0xbfb8aa3b, v50
	v_mul_f32_e32 v58, 0xbfb8aa3b, v57
	v_exp_f32_e32 v51, v51
	v_exp_f32_e32 v58, v58
	v_add_f32_e32 v51, 1.0, v51
	v_add_f32_e32 v58, 1.0, v58
	v_div_scale_f32 v52, s[8:9], v51, v51, v50
	v_div_scale_f32 v59, s[8:9], v58, v58, v57
	v_rcp_f32_e32 v53, v52
	v_rcp_f32_e32 v60, v59
	v_fma_f32 v54, -v52, v53, 1.0
	v_fma_f32 v61, -v59, v60, 1.0
	v_fmac_f32_e32 v53, v54, v53
	v_fmac_f32_e32 v60, v61, v60
	v_div_scale_f32 v55, vcc, v50, v51, v50
	v_mul_f32_e32 v56, v55, v53
	v_fma_f32 v54, -v52, v56, v55
	v_fmac_f32_e32 v56, v54, v53
	v_fma_f32 v52, -v52, v56, v55
	v_div_fmas_f32 v52, v52, v53, v56
	v_div_fixup_f32 v52, v52, v51, v50
	v_mul_f32_e32 v23, v23, v52
	v_div_scale_f32 v62, vcc, v57, v58, v57
	v_mul_f32_e32 v63, v62, v60
	v_fma_f32 v61, -v59, v63, v62
	v_fmac_f32_e32 v63, v61, v60
	v_fma_f32 v59, -v59, v63, v62
	v_div_fmas_f32 v59, v59, v60, v63
	v_div_fixup_f32 v59, v59, v58, v57
	v_mul_f32_e32 v25, v25, v59
	v_cvt_pk_bf16_f32 v222, v23, v25
	v_lshlrev_b32_e32 v50, 16, v231
	v_and_b32_e32 v57, 0xffff0000, v231
	v_mul_f32_e32 v51, 0xbfb8aa3b, v50
	v_mul_f32_e32 v58, 0xbfb8aa3b, v57
	v_exp_f32_e32 v51, v51
	v_exp_f32_e32 v58, v58
	v_add_f32_e32 v51, 1.0, v51
	v_add_f32_e32 v58, 1.0, v58
	v_div_scale_f32 v52, s[8:9], v51, v51, v50
	v_div_scale_f32 v59, s[8:9], v58, v58, v57
	v_rcp_f32_e32 v53, v52
	v_rcp_f32_e32 v60, v59
	v_fma_f32 v54, -v52, v53, 1.0
	v_fma_f32 v61, -v59, v60, 1.0
	v_fmac_f32_e32 v53, v54, v53
	v_fmac_f32_e32 v60, v61, v60
	v_div_scale_f32 v55, vcc, v50, v51, v50
	v_mul_f32_e32 v56, v55, v53
	v_fma_f32 v54, -v52, v56, v55
	v_fmac_f32_e32 v56, v54, v53
	v_fma_f32 v52, -v52, v56, v55
	v_div_fmas_f32 v52, v52, v53, v56
	v_div_fixup_f32 v52, v52, v51, v50
	v_mul_f32_e32 v27, v27, v52
	v_div_scale_f32 v62, vcc, v57, v58, v57
	v_mul_f32_e32 v63, v62, v60
	v_fma_f32 v61, -v59, v63, v62
	v_fmac_f32_e32 v63, v61, v60
	v_fma_f32 v59, -v59, v63, v62
	v_div_fmas_f32 v59, v59, v60, v63
	v_div_fixup_f32 v59, v59, v58, v57
	v_mul_f32_e32 v29, v29, v59
	v_cvt_pk_bf16_f32 v223, v27, v29
	v_lshlrev_b32_e32 v50, 16, v232
	v_and_b32_e32 v57, 0xffff0000, v232
	v_mul_f32_e32 v51, 0xbfb8aa3b, v50
	v_mul_f32_e32 v58, 0xbfb8aa3b, v57
	v_exp_f32_e32 v51, v51
	v_exp_f32_e32 v58, v58
	v_add_f32_e32 v51, 1.0, v51
	v_add_f32_e32 v58, 1.0, v58
	v_div_scale_f32 v52, s[8:9], v51, v51, v50
	v_div_scale_f32 v59, s[8:9], v58, v58, v57
	v_rcp_f32_e32 v53, v52
	v_rcp_f32_e32 v60, v59
	v_fma_f32 v54, -v52, v53, 1.0
	v_fma_f32 v61, -v59, v60, 1.0
	v_fmac_f32_e32 v53, v54, v53
	v_fmac_f32_e32 v60, v61, v60
	v_div_scale_f32 v55, vcc, v50, v51, v50
	v_mul_f32_e32 v56, v55, v53
	v_fma_f32 v54, -v52, v56, v55
	v_fmac_f32_e32 v56, v54, v53
	v_fma_f32 v52, -v52, v56, v55
	v_div_fmas_f32 v52, v52, v53, v56
	v_div_fixup_f32 v52, v52, v51, v50
	v_mul_f32_e32 v31, v31, v52
	v_div_scale_f32 v62, vcc, v57, v58, v57
	v_mul_f32_e32 v63, v62, v60
	v_fma_f32 v61, -v59, v63, v62
	v_fmac_f32_e32 v63, v61, v60
	v_fma_f32 v59, -v59, v63, v62
	v_div_fmas_f32 v59, v59, v60, v63
	v_div_fixup_f32 v59, v59, v58, v57
	v_mul_f32_e32 v33, v33, v59
	v_cvt_pk_bf16_f32 v224, v31, v33
	v_lshlrev_b32_e32 v50, 16, v233
	v_and_b32_e32 v57, 0xffff0000, v233
	v_mul_f32_e32 v51, 0xbfb8aa3b, v50
	v_mul_f32_e32 v58, 0xbfb8aa3b, v57
	v_exp_f32_e32 v51, v51
	v_exp_f32_e32 v58, v58
	v_add_f32_e32 v51, 1.0, v51
	v_add_f32_e32 v58, 1.0, v58
	v_div_scale_f32 v52, s[8:9], v51, v51, v50
	v_div_scale_f32 v59, s[8:9], v58, v58, v57
	v_rcp_f32_e32 v53, v52
	v_rcp_f32_e32 v60, v59
	v_fma_f32 v54, -v52, v53, 1.0
	v_fma_f32 v61, -v59, v60, 1.0
	v_fmac_f32_e32 v53, v54, v53
	v_fmac_f32_e32 v60, v61, v60
	v_div_scale_f32 v55, vcc, v50, v51, v50
	v_mul_f32_e32 v56, v55, v53
	v_fma_f32 v54, -v52, v56, v55
	v_fmac_f32_e32 v56, v54, v53
	v_fma_f32 v52, -v52, v56, v55
	v_div_fmas_f32 v52, v52, v53, v56
	v_div_fixup_f32 v52, v52, v51, v50
	v_mul_f32_e32 v35, v35, v52
	v_div_scale_f32 v62, vcc, v57, v58, v57
	v_mul_f32_e32 v63, v62, v60
	v_fma_f32 v61, -v59, v63, v62
	v_fmac_f32_e32 v63, v61, v60
	v_fma_f32 v59, -v59, v63, v62
	v_div_fmas_f32 v59, v59, v60, v63
	v_div_fixup_f32 v59, v59, v58, v57
	v_mul_f32_e32 v37, v37, v59
	v_cvt_pk_bf16_f32 v225, v35, v37
	v_lshlrev_b32_e32 v50, 16, v238
	v_and_b32_e32 v57, 0xffff0000, v238
	v_mul_f32_e32 v51, 0xbfb8aa3b, v50
	v_mul_f32_e32 v58, 0xbfb8aa3b, v57
	v_exp_f32_e32 v51, v51
	v_exp_f32_e32 v58, v58
	v_add_f32_e32 v51, 1.0, v51
	v_add_f32_e32 v58, 1.0, v58
	v_div_scale_f32 v52, s[8:9], v51, v51, v50
	v_div_scale_f32 v59, s[8:9], v58, v58, v57
	v_rcp_f32_e32 v53, v52
	v_rcp_f32_e32 v60, v59
	v_fma_f32 v54, -v52, v53, 1.0
	v_fma_f32 v61, -v59, v60, 1.0
	v_fmac_f32_e32 v53, v54, v53
	v_fmac_f32_e32 v60, v61, v60
	v_div_scale_f32 v55, vcc, v50, v51, v50
	v_mul_f32_e32 v56, v55, v53
	v_fma_f32 v54, -v52, v56, v55
	v_fmac_f32_e32 v56, v54, v53
	v_fma_f32 v52, -v52, v56, v55
	v_div_fmas_f32 v52, v52, v53, v56
	v_div_fixup_f32 v52, v52, v51, v50
	v_mul_f32_e32 v22, v22, v52
	v_div_scale_f32 v62, vcc, v57, v58, v57
	v_mul_f32_e32 v63, v62, v60
	v_fma_f32 v61, -v59, v63, v62
	v_fmac_f32_e32 v63, v61, v60
	v_fma_f32 v59, -v59, v63, v62
	v_div_fmas_f32 v59, v59, v60, v63
	v_div_fixup_f32 v59, v59, v58, v57
	v_mul_f32_e32 v24, v24, v59
	v_cvt_pk_bf16_f32 v230, v22, v24
	v_lshlrev_b32_e32 v50, 16, v239
	v_and_b32_e32 v57, 0xffff0000, v239
	v_mul_f32_e32 v51, 0xbfb8aa3b, v50
	v_mul_f32_e32 v58, 0xbfb8aa3b, v57
	v_exp_f32_e32 v51, v51
	v_exp_f32_e32 v58, v58
	v_add_f32_e32 v51, 1.0, v51
	v_add_f32_e32 v58, 1.0, v58
	v_div_scale_f32 v52, s[8:9], v51, v51, v50
	v_div_scale_f32 v59, s[8:9], v58, v58, v57
	v_rcp_f32_e32 v53, v52
	v_rcp_f32_e32 v60, v59
	v_fma_f32 v54, -v52, v53, 1.0
	v_fma_f32 v61, -v59, v60, 1.0
	v_fmac_f32_e32 v53, v54, v53
	v_fmac_f32_e32 v60, v61, v60
	v_div_scale_f32 v55, vcc, v50, v51, v50
	v_mul_f32_e32 v56, v55, v53
	v_fma_f32 v54, -v52, v56, v55
	v_fmac_f32_e32 v56, v54, v53
	v_fma_f32 v52, -v52, v56, v55
	v_div_fmas_f32 v52, v52, v53, v56
	v_div_fixup_f32 v52, v52, v51, v50
	v_mul_f32_e32 v26, v26, v52
	v_div_scale_f32 v62, vcc, v57, v58, v57
	v_mul_f32_e32 v63, v62, v60
	v_fma_f32 v61, -v59, v63, v62
	v_fmac_f32_e32 v63, v61, v60
	v_fma_f32 v59, -v59, v63, v62
	v_div_fmas_f32 v59, v59, v60, v63
	v_div_fixup_f32 v59, v59, v58, v57
	v_mul_f32_e32 v28, v28, v59
	v_cvt_pk_bf16_f32 v231, v26, v28
	v_lshlrev_b32_e32 v50, 16, v240
	v_and_b32_e32 v57, 0xffff0000, v240
	v_mul_f32_e32 v51, 0xbfb8aa3b, v50
	v_mul_f32_e32 v58, 0xbfb8aa3b, v57
	v_exp_f32_e32 v51, v51
	v_exp_f32_e32 v58, v58
	v_add_f32_e32 v51, 1.0, v51
	v_add_f32_e32 v58, 1.0, v58
	v_div_scale_f32 v52, s[8:9], v51, v51, v50
	v_div_scale_f32 v59, s[8:9], v58, v58, v57
	v_rcp_f32_e32 v53, v52
	v_rcp_f32_e32 v60, v59
	v_fma_f32 v54, -v52, v53, 1.0
	v_fma_f32 v61, -v59, v60, 1.0
	v_fmac_f32_e32 v53, v54, v53
	v_fmac_f32_e32 v60, v61, v60
	v_div_scale_f32 v55, vcc, v50, v51, v50
	v_mul_f32_e32 v56, v55, v53
	v_fma_f32 v54, -v52, v56, v55
	v_fmac_f32_e32 v56, v54, v53
	v_fma_f32 v52, -v52, v56, v55
	v_div_fmas_f32 v52, v52, v53, v56
	v_div_fixup_f32 v52, v52, v51, v50
	v_mul_f32_e32 v30, v30, v52
	v_div_scale_f32 v62, vcc, v57, v58, v57
	v_mul_f32_e32 v63, v62, v60
	v_fma_f32 v61, -v59, v63, v62
	v_fmac_f32_e32 v63, v61, v60
	v_fma_f32 v59, -v59, v63, v62
	v_div_fmas_f32 v59, v59, v60, v63
	v_div_fixup_f32 v59, v59, v58, v57
	v_mul_f32_e32 v32, v32, v59
	v_cvt_pk_bf16_f32 v232, v30, v32
	v_lshlrev_b32_e32 v50, 16, v241
	v_and_b32_e32 v57, 0xffff0000, v241
	v_mul_f32_e32 v51, 0xbfb8aa3b, v50
	v_mul_f32_e32 v58, 0xbfb8aa3b, v57
	v_exp_f32_e32 v51, v51
	v_exp_f32_e32 v58, v58
	v_add_f32_e32 v51, 1.0, v51
	v_add_f32_e32 v58, 1.0, v58
	v_div_scale_f32 v52, s[8:9], v51, v51, v50
	v_div_scale_f32 v59, s[8:9], v58, v58, v57
	v_rcp_f32_e32 v53, v52
	v_rcp_f32_e32 v60, v59
	v_fma_f32 v54, -v52, v53, 1.0
	v_fma_f32 v61, -v59, v60, 1.0
	v_fmac_f32_e32 v53, v54, v53
	v_fmac_f32_e32 v60, v61, v60
	v_div_scale_f32 v55, vcc, v50, v51, v50
	v_mul_f32_e32 v56, v55, v53
	v_fma_f32 v54, -v52, v56, v55
	v_fmac_f32_e32 v56, v54, v53
	v_fma_f32 v52, -v52, v56, v55
	v_div_fmas_f32 v52, v52, v53, v56
	v_div_fixup_f32 v52, v52, v51, v50
	v_mul_f32_e32 v34, v34, v52
	v_div_scale_f32 v62, vcc, v57, v58, v57
	v_mul_f32_e32 v63, v62, v60
	v_fma_f32 v61, -v59, v63, v62
	v_fmac_f32_e32 v63, v61, v60
	v_fma_f32 v59, -v59, v63, v62
	v_div_fmas_f32 v59, v59, v60, v63
	v_div_fixup_f32 v59, v59, v58, v57
	v_mul_f32_e32 v36, v36, v59
	v_cvt_pk_bf16_f32 v233, v34, v36
	global_store_dwordx4 v[252:253], v[222:225], off offset:1024
	global_store_dwordx4 v[252:253], v[230:233], off offset:3072
	s_addk_i32 s0, 0x810
	s_cmpk_eq_i32 s0, 0x4080
	s_cbranch_scc0 .Lmg_loop
	v_readfirstlane_b32 s8, v167
	s_mov_b64 s[10:11], exec
	v_readlane_b32 s0, v254, 48
	v_readlane_b32 s1, v254, 49
	s_and_b64 s[0:1], s[10:11], s[0:1]
	s_mov_b64 exec, s[0:1]
	s_cbranch_execz .LBB0_1086
	s_mov_b64 s[0:1], exec
	s_lshr_b32 s8, s8, 4
	s_and_b32 s8, s8, 0xffffff0
	v_mbcnt_lo_u32_b32 v0, s0, 0
	s_add_i32 s20, s8, 0
	v_mbcnt_hi_u32_b32 v0, s1, v0
	s_add_i32 s20, s20, 0x220c0
	v_cmp_eq_u32_e32 vcc, 0, v0
	s_and_saveexec_b64 s[8:9], vcc
	s_bcnt1_i32_b64 s0, s[0:1]
	v_mov_b32_e32 v1, s20
	v_mov_b32_e32 v2, s0
	ds_add_rtn_u32 v1, v1, v2
	s_or_b64 exec, exec, s[8:9]
	s_waitcnt lgkmcnt(0)
	v_readfirstlane_b32 s0, v1
	v_mov_b32_e32 v1, s20
	ds_read_b32 v1, v1
	v_add_u32_e32 v0, s0, v0
	v_bitop3_b32 v0, v0, -4, v0 bitop3:0xc
	s_waitcnt lgkmcnt(0)
	v_add_u32_e32 v1, v0, v1
	v_cmp_gt_i32_e32 vcc, 0, v1
	s_and_b64 exec, exec, vcc
	s_cbranch_execz .LBB0_1086
	s_mov_b64 s[0:1], 0
